# row128 LDS image (128-byte rows, xor-swizzled chunks, whole-line DMA pieces) for the P6 K-loop
# baseline (speedup 1.0000x reference)
.LBB0_837:
	s_or_b64 exec, exec, s[0:1]
	v_mov_b32_e32 v9, v252
	s_waitcnt lgkmcnt(0)
	s_barrier
	s_cmpk_lt_i32 s50, 0x580
	s_nop 0
	v_readfirstlane_b32 s16, v9
	s_cbranch_scc0 .LBB0_853
	v_lshlrev_b32_e32 v0, 4, v9
	v_add_u32_e32 v1, 0x2000, v0
	v_ashrrev_i32_e32 v2, 31, v1
	v_lshrrev_b32_e32 v2, 22, v2
	v_add_u32_e32 v2, v1, v2
	v_ashrrev_i32_e32 v8, 10, v2
	v_mul_i32_i24_e32 v2, 0x400, v8
	v_sub_u32_e32 v1, v1, v2
	v_lshrrev_b32_e32 v2, 4, v1
	v_bitop3_b32 v1, v2, v1, 32 bitop3:0x6c
	v_ashrrev_i32_e32 v2, 31, v1
	v_lshrrev_b32_e32 v2, 26, v2
	v_add_u32_e32 v2, v1, v2
	v_lshlrev_b32_e32 v3, 3, v8
	v_ashrrev_i32_e32 v10, 6, v2
	v_and_b32_e32 v3, -16, v3
	v_add_u32_e32 v3, v10, v3
	v_and_b32_e32 v4, 3, v10
	s_mov_b32 s0, 0xfffe0
	v_lshrrev_b32_e32 v5, 2, v3
	v_lshlrev_b32_e32 v6, 1, v3
	v_and_b32_e32 v2, 0xc0, v2
	v_and_or_b32 v4, v3, s0, v4
	v_and_b32_e32 v5, 4, v5
	v_and_b32_e32 v6, 24, v6
	v_sub_u32_e32 v1, v1, v2
	v_mov_b32_e32 v2, 1
	v_or3_b32 v4, v4, v5, v6
	v_lshlrev_b32_e32 v5, 5, v8
	v_ashrrev_i16_sdwa v1, v2, sext(v1) dst_sel:DWORD dst_unused:UNUSED_PAD src0_sel:DWORD src1_sel:BYTE_0
	v_and_b32_e32 v5, 32, v5
	v_bfe_i32 v11, v1, 0, 16
	v_add_lshl_u32 v1, v5, v11, 1
	v_lshl_add_u32 v144, v4, 12, v1
	v_lshl_add_u32 v146, v3, 12, v1
	v_bfe_i32 v1, v9, 27, 1
	v_lshrrev_b32_e32 v1, 22, v1
	v_add_u32_e32 v1, v0, v1
	v_and_b32_e32 v1, 0xfffffc00, v1
	v_sub_u32_e32 v0, v0, v1
	v_lshrrev_b32_e32 v1, 4, v0
	v_ashrrev_i32_e32 v3, 31, v9
	v_bitop3_b32 v0, v1, v0, 32 bitop3:0x6c
	v_lshrrev_b32_e32 v3, 26, v3
	v_ashrrev_i32_e32 v1, 31, v0
	v_add_u32_e32 v3, v9, v3
	v_lshrrev_b32_e32 v1, 26, v1
	v_ashrrev_i32_e32 v13, 6, v3
	v_add_u32_e32 v1, v0, v1
	v_lshlrev_b32_e32 v3, 3, v13
	v_ashrrev_i32_e32 v12, 6, v1
	v_and_b32_e32 v3, -16, v3
	v_add_u32_e32 v3, v12, v3
	v_and_b32_e32 v4, 3, v12
	v_and_or_b32 v4, v3, s0, v4
	s_lshr_b32 s0, s33, 29
	s_add_i32 s0, s50, s0
	s_ashr_i32 s6, s16, 6
	s_ashr_i32 s1, s0, 3
	s_and_b32 s0, s0, -8
	s_ashr_i32 s17, s16, 8
	s_lshl_b32 s2, s6, 10
	s_sub_i32 s0, s50, s0
	s_cmp_lt_i32 s0, 0
	s_movk_i32 s36, 0xb1
	s_cselect_b32 s4, s36, 0xb0
	s_mul_i32 s0, s0, s4
	s_add_i32 s0, s0, s1
	s_mul_hi_i32 s1, s0, 0x2e8ba2e9
	s_lshr_b32 s4, s1, 31
	s_ashr_i32 s1, s1, 6
	s_add_i32 s1, s1, s4
	s_lshl_b32 s4, s1, 3
	s_mulk_i32 s1, 0x160
	s_sub_i32 s1, s0, s1
	s_sext_i32_i16 s0, s1
	s_bfe_u32 s0, s0, 0x3001c
	s_add_i32 s5, s1, s0
	s_sext_i32_i16 s0, s5
	s_and_b32 s5, s5, 0xfff8
	s_sub_i32 s1, s1, s5
	s_sext_i32_i16 s1, s1
	v_lshrrev_b32_e32 v5, 2, v3
	v_lshlrev_b32_e32 v6, 1, v3
	v_and_b32_e32 v1, 0xc0, v1
	s_lshr_b32 s0, s0, 3
	s_add_i32 s10, s4, s1
	v_and_b32_e32 v5, 4, v5
	v_and_b32_e32 v6, 24, v6
	v_sub_u32_e32 v0, v0, v1
	s_ashr_i32 s11, s10, 31
	s_bfe_i64 s[12:13], s[0:1], 0x100000
	v_or3_b32 v4, v4, v5, v6
	v_lshlrev_b32_e32 v5, 5, v13
	v_ashrrev_i16_sdwa v0, v2, sext(v0) dst_sel:DWORD dst_unused:UNUSED_PAD src0_sel:DWORD src1_sel:BYTE_0
	s_lshl_b64 s[4:5], s[10:11], 20
	s_lshl_b64 s[12:13], s[12:13], 20
	v_readlane_b32 s22, v255, 21
	v_and_b32_e32 v5, 32, v5
	v_bfe_i32 v14, v0, 0, 16
	v_readlane_b32 s23, v255, 22
	s_add_u32 s30, s22, s12
	v_add_lshl_u32 v0, v5, v14, 1
	s_addc_u32 s31, s23, s13
	s_add_i32 s37, s2, 0
	v_lshl_add_u32 v148, v4, 12, v0
	s_add_i32 m0, s37, 0x10000
	v_lshl_add_u32 v150, v3, 12, v0
	s_nop 0
	s_add_i32 m0, s37, 0x12000
	s_add_u32 s12, s30, 0x80000
	s_nop 0
	s_addc_u32 s13, s31, 0
	s_add_i32 m0, s37, 0x14000
	v_mov_b32_e32 v153, 0
	s_nop 0
	s_add_i32 m0, s37, 0x16000
	v_mov_b32_e32 v149, v153
	s_nop 0
	s_add_u32 s12, s20, s4
	s_addc_u32 s13, s21, s5
	s_add_i32 s42, s37, 0x2000
	s_mov_b32 m0, s37
	s_add_u32 s4, s12, 0x80000
	s_nop 0
	s_mov_b32 m0, s42
	s_addc_u32 s5, s13, 0
	s_add_i32 s43, s37, 0x4000
	s_nop 0
	s_mov_b32 m0, s43
	s_add_i32 s44, s37, 0x6000
	s_nop 0
	s_mov_b32 m0, s44
	v_mov_b32_e32 v145, v153
	s_nop 0
	v_and_b32_e32 v220, 63, v252
	v_and_b32_e32 v221, 15, v220
	v_lshrrev_b32_e32 v222, 4, v220
	v_bfe_u32 v223, v220, 1, 3
	v_xor_b32_e32 v222, v222, v223
	v_lshlrev_b32_e32 v222, 4, v222
	v_lshl_add_u32 v222, v221, 7, v222
	s_lshr_b32 vcc_lo, s37, 12
	s_lshl_b32 vcc_lo, vcc_lo, 13
	v_add_u32_e32 v171, vcc_lo, v222
	v_xor_b32_e32 v146, 64, v171
	s_and_b32 vcc_lo, s37, 0xc00
	s_lshl_b32 vcc_lo, vcc_lo, 2
	s_add_i32 vcc_lo, vcc_lo, 0x10000
	v_add_u32_e32 v169, vcc_lo, v222
	v_xor_b32_e32 v170, 64, v169
	v_lshrrev_b32_e32 v221, 4, v220
	s_bfe_u32 vcc_lo, s37, 0x1000a
	s_lshl_b32 vcc_lo, vcc_lo, 2
	v_add_u32_e32 v221, vcc_lo, v221
	v_and_b32_e32 v223, 7, v220
	v_xor_b32_e32 v221, v221, v223
	v_lshlrev_b32_e32 v221, 4, v221
	v_lshrrev_b32_e32 v222, 3, v220
	s_and_b32 vcc_lo, s37, 0xc00
	s_lshr_b32 vcc_lo, vcc_lo, 7
	v_add_u32_e32 v222, vcc_lo, v222
	v_mul_u32_u24_e32 v222, 0x1000, v222
	v_add_u32_e32 v150, v222, v221
	v_lshrrev_b32_e32 v222, 5, v220
	v_lshlrev_b32_e32 v222, 3, v222
	v_bfe_u32 v223, v220, 3, 2
	v_add_u32_e32 v222, v222, v223
	s_bfe_u32 vcc_lo, s37, 0x1000a
	s_lshl_b32 vcc_lo, vcc_lo, 4
	s_bfe_u32 vcc_hi, s37, 0x1000b
	s_lshl_b32 vcc_hi, vcc_hi, 2
	s_add_i32 vcc_lo, vcc_lo, vcc_hi
	v_add_u32_e32 v222, vcc_lo, v222
	v_mul_u32_u24_e32 v222, 0x1000, v222
	v_add_u32_e32 v148, v222, v221
	s_cmp_lt_u32 s37, 0x1000
	s_cbranch_scc0 .Lr128_pt_p6
	s_add_u32 vcc_lo, s30, 0x0
	s_addc_u32 vcc_hi, s31, 0
	s_add_i32 m0, s37, 0x10000
	s_nop 0
	global_load_lds_dwordx4 v148, vcc
	s_add_u32 vcc_lo, vcc_lo, 0x20000
	s_addc_u32 vcc_hi, vcc_hi, 0
	s_add_i32 m0, s37, 0x11000
	s_nop 0
	global_load_lds_dwordx4 v148, vcc
	s_add_u32 vcc_lo, vcc_lo, 0x20000
	s_addc_u32 vcc_hi, vcc_hi, 0
	s_add_i32 m0, s37, 0x12000
	s_nop 0
	global_load_lds_dwordx4 v148, vcc
	s_add_u32 vcc_lo, vcc_lo, 0x20000
	s_addc_u32 vcc_hi, vcc_hi, 0
	s_add_i32 m0, s37, 0x13000
	s_nop 0
	global_load_lds_dwordx4 v148, vcc
	s_add_u32 vcc_lo, vcc_lo, 0x20000
	s_addc_u32 vcc_hi, vcc_hi, 0
	s_add_i32 m0, s37, 0x14000
	s_nop 0
	global_load_lds_dwordx4 v148, vcc
	s_add_u32 vcc_lo, vcc_lo, 0x20000
	s_addc_u32 vcc_hi, vcc_hi, 0
	s_add_i32 m0, s37, 0x15000
	s_nop 0
	global_load_lds_dwordx4 v148, vcc
	s_add_u32 vcc_lo, vcc_lo, 0x20000
	s_addc_u32 vcc_hi, vcc_hi, 0
	s_add_i32 m0, s37, 0x16000
	s_nop 0
	global_load_lds_dwordx4 v148, vcc
	s_add_u32 vcc_lo, vcc_lo, 0x20000
	s_addc_u32 vcc_hi, vcc_hi, 0
	s_add_i32 m0, s37, 0x17000
	s_nop 0
	global_load_lds_dwordx4 v148, vcc
	s_branch .Lr128_pd_p6
.Lr128_pt_p6:
	s_add_u32 vcc_lo, s12, 0x0
	s_addc_u32 vcc_hi, s13, 0
	s_sub_i32 m0, s37, 0x1000
	s_nop 0
	global_load_lds_dwordx4 v150, vcc
	s_add_u32 vcc_lo, vcc_lo, 0x20000
	s_addc_u32 vcc_hi, vcc_hi, 0
	s_mov_b32 m0, s37
	s_nop 0
	global_load_lds_dwordx4 v150, vcc
	s_add_u32 vcc_lo, vcc_lo, 0x20000
	s_addc_u32 vcc_hi, vcc_hi, 0
	s_add_i32 m0, s37, 0x1000
	s_nop 0
	global_load_lds_dwordx4 v150, vcc
	s_add_u32 vcc_lo, vcc_lo, 0x20000
	s_addc_u32 vcc_hi, vcc_hi, 0
	s_add_i32 m0, s37, 0x2000
	s_nop 0
	global_load_lds_dwordx4 v150, vcc
	s_add_u32 vcc_lo, vcc_lo, 0x20000
	s_addc_u32 vcc_hi, vcc_hi, 0
	s_add_i32 m0, s37, 0x3000
	s_nop 0
	global_load_lds_dwordx4 v150, vcc
	s_add_u32 vcc_lo, vcc_lo, 0x20000
	s_addc_u32 vcc_hi, vcc_hi, 0
	s_add_i32 m0, s37, 0x4000
	s_nop 0
	global_load_lds_dwordx4 v150, vcc
	s_add_u32 vcc_lo, vcc_lo, 0x20000
	s_addc_u32 vcc_hi, vcc_hi, 0
	s_add_i32 m0, s37, 0x5000
	s_nop 0
	global_load_lds_dwordx4 v150, vcc
	s_add_u32 vcc_lo, vcc_lo, 0x20000
	s_addc_u32 vcc_hi, vcc_hi, 0
	s_add_i32 m0, s37, 0x6000
	s_nop 0
	global_load_lds_dwordx4 v150, vcc
.Lr128_pd_p6:
	v_mov_b32_e32 v151, v153
	v_mov_b32_e32 v147, v153
	s_cmp_eq_u32 s17, 1
	s_mov_b32 s1, 0
	v_lshl_add_u64 v[6:7], s[30:31], 0, v[148:149]
	v_lshl_add_u64 v[4:5], s[30:31], 0, v[144:145]
	v_lshl_add_u64 v[0:1], s[12:13], 0, v[150:151]
	s_cselect_b64 s[4:5], -1, 0
	s_cmp_lg_u32 s17, 1
	v_lshl_add_u64 v[2:3], s[12:13], 0, v[146:147]
	s_cbranch_scc1 .LBB0_840
	s_barrier
.LBB0_840:
	s_lshl_b32 s6, s6, 5
	s_and_b32 s25, s6, 0x60
	s_mov_b64 s[6:7], 0x80
	s_add_i32 m0, s37, 0x18000
	v_lshl_add_u64 v[6:7], v[6:7], 0, s[6:7]
	s_lshl_b32 s24, s17, 13
	s_lshl_b32 s26, s25, 7
	s_waitcnt vmcnt(0)
	s_barrier
	s_cmp_lt_u32 s37, 0x1000
	s_cbranch_scc1 .Lr128_p2_p6
	s_add_u32 vcc_lo, s12, 0x80
	s_addc_u32 vcc_hi, s13, 0
	s_add_i32 m0, s37, 0x7000
	s_nop 0
	global_load_lds_dwordx4 v150, vcc
	s_add_u32 vcc_lo, vcc_lo, 0x20000
	s_addc_u32 vcc_hi, vcc_hi, 0
	s_add_i32 m0, s37, 0x8000
	s_nop 0
	global_load_lds_dwordx4 v150, vcc
	s_add_u32 vcc_lo, vcc_lo, 0x60000
	s_addc_u32 vcc_hi, vcc_hi, 0
	s_add_i32 m0, s37, 0xb000
	s_nop 0
	global_load_lds_dwordx4 v150, vcc
	s_add_u32 vcc_lo, vcc_lo, 0x20000
	s_addc_u32 vcc_hi, vcc_hi, 0
	s_add_i32 m0, s37, 0xc000
	s_nop 0
	global_load_lds_dwordx4 v150, vcc
.Lr128_p2_p6:
	s_nop 0
	v_lshl_add_u64 v[4:5], v[4:5], 0, s[6:7]
	s_add_i32 m0, s37, 0x1a000
	s_add_i32 s45, s37, 0x8000
	s_add_i32 s46, s37, 0xa000
	s_nop 0
	v_lshl_add_u64 v[0:1], v[0:1], 0, s[6:7]
	s_mov_b32 m0, s45
	s_add_u32 s22, s30, 0x80080
	s_nop 0
	v_lshl_add_u64 v[0:1], v[2:3], 0, s[6:7]
	s_mov_b32 m0, s46
	s_addc_u32 s23, s31, 0
	s_nop 0
	s_add_i32 m0, s37, 0x1c000
	v_lshl_add_u64 v[0:1], s[22:23], 0, v[148:149]
	s_nop 0
	v_lshl_add_u64 v[0:1], s[22:23], 0, v[144:145]
	s_add_i32 m0, s37, 0x1e000
	s_cmpk_lt_u32 s16, 0x100
	s_nop 0
	v_lshrrev_b32_e32 v0, 1, v9
	v_and_b32_e32 v0, 24, v0
	v_and_b32_e32 v1, 15, v9
	v_lshlrev_b32_e32 v2, 1, v0
	v_lshl_or_b32 v166, s17, 6, v1
	v_lshl_or_b32 v1, v1, 6, v2
	v_lshlrev_b32_e32 v2, 2, v9
	v_and_b32_e32 v2, 32, v2
	v_bitop3_b32 v3, v1, s24, v2 bitop3:0xde
	v_bitop3_b32 v167, v1, s26, v2 bitop3:0xde
	v_lshlrev_b32_e32 v1, 15, v13
	v_and_b32_e32 v1, 0xffff0000, v1
	v_lshl_add_u32 v1, v12, 12, v1
	v_and_b32_e32 v2, 1, v13
	v_lshl_or_b32 v1, v2, 6, v1
	v_lshl_add_u32 v154, v14, 1, v1
	v_lshlrev_b32_e32 v1, 15, v8
	v_and_b32_e32 v1, 0xffff0000, v1
	s_waitcnt vmcnt(6)
	v_lshl_add_u32 v1, v10, 12, v1
	v_and_b32_e32 v2, 1, v8
	s_cselect_b64 s[16:17], -1, 0
	v_lshl_or_b32 v1, v2, 6, v1
	s_add_i32 s47, 0, 0x10000
	s_add_i32 s48, 0, 0x14000
	s_sext_i32_i16 s11, s0
	v_or_b32_e32 v168, s25, v0
	v_mov_b32_e32 v155, v153
	v_lshl_add_u32 v156, v11, 1, v1
	v_mov_b32_e32 v157, v153
	v_mov_b64_e32 v[158:159], 0x580
	v_mov_b64_e32 v[160:161], 0x57f
	s_nop 0
	s_nop 0
	s_nop 0
	v_mov_b32_e32 v172, 0x358637bd
	s_movk_i32 s49, 0x2c00
	s_lshl_b32 s0, s25, 1
	v_lshlrev_b32_e32 v152, 1, v0
	s_mov_b32 s51, s1
	s_barrier
	s_branch .LBB0_843

.LBB0_846:
	s_add_u32 s30, s12, 0xfff80080
	s_addc_u32 s31, s13, -1
	s_cmp_eq_u32 s56, 28
	s_cselect_b32 s35, s25, s31
	s_cselect_b32 s34, s52, s30
	s_cselect_b32 s31, s23, s55
	s_cselect_b32 s30, s53, s54
	s_and_b64 vcc, exec, s[16:17]
	s_cbranch_vccz .Lk64_trail_p6
	s_sub_u32 vcc_lo, s54, 0x80
	s_subb_u32 vcc_hi, s55, 0
	s_add_i32 m0, s37, 0x18000
	s_nop 0
	global_load_lds_dwordx4 v148, vcc
	s_add_u32 vcc_lo, vcc_lo, 0x20000
	s_addc_u32 vcc_hi, vcc_hi, 0
	s_add_i32 m0, s37, 0x19000
	s_nop 0
	global_load_lds_dwordx4 v148, vcc
	s_add_u32 vcc_lo, vcc_lo, 0x20000
	s_addc_u32 vcc_hi, vcc_hi, 0
	s_add_i32 m0, s37, 0x1a000
	s_nop 0
	global_load_lds_dwordx4 v148, vcc
	s_add_u32 vcc_lo, vcc_lo, 0x20000
	s_addc_u32 vcc_hi, vcc_hi, 0
	s_add_i32 m0, s37, 0x1b000
	s_nop 0
	global_load_lds_dwordx4 v148, vcc
	s_add_u32 vcc_lo, vcc_lo, 0x20000
	s_addc_u32 vcc_hi, vcc_hi, 0
	s_add_i32 m0, s37, 0x1c000
	s_nop 0
	global_load_lds_dwordx4 v148, vcc
	s_add_u32 vcc_lo, vcc_lo, 0x20000
	s_addc_u32 vcc_hi, vcc_hi, 0
	s_add_i32 m0, s37, 0x1d000
	s_nop 0
	global_load_lds_dwordx4 v148, vcc
	s_add_u32 vcc_lo, vcc_lo, 0x20000
	s_addc_u32 vcc_hi, vcc_hi, 0
	s_add_i32 m0, s37, 0x1e000
	s_nop 0
	global_load_lds_dwordx4 v148, vcc
	s_add_u32 vcc_lo, vcc_lo, 0x20000
	s_addc_u32 vcc_hi, vcc_hi, 0
	s_add_i32 m0, s37, 0x1f000
	s_nop 0
	global_load_lds_dwordx4 v148, vcc
	ds_read_b128 v[32:35], v169 offset:0
	ds_read_b128 v[36:39], v170 offset:0
	ds_read_b128 v[40:43], v169 offset:2048
	ds_read_b128 v[44:47], v170 offset:2048
	ds_read_b128 v[162:165], v169 offset:16384
	ds_read_b128 v[174:177], v170 offset:16384
	ds_read_b128 v[178:181], v169 offset:18432
	ds_read_b128 v[182:185], v170 offset:18432
	ds_read_b128 v[186:189], v171 offset:0
	ds_read_b128 v[190:193], v146 offset:0
	ds_read_b128 v[194:197], v171 offset:2048
	ds_read_b128 v[198:201], v146 offset:2048
	ds_read_b128 v[202:205], v171 offset:4096
	ds_read_b128 v[206:209], v146 offset:4096
	ds_read_b128 v[210:213], v171 offset:6144
	ds_read_b128 v[214:217], v146 offset:6144
	ds_read_b128 v[220:223], v171 offset:16384
	ds_read_b128 v[224:227], v146 offset:16384
	ds_read_b128 v[228:231], v171 offset:18432
	ds_read_b128 v[232:235], v146 offset:18432
	ds_read_b128 v[236:239], v171 offset:20480
	ds_read_b128 v[240:243], v146 offset:20480
	ds_read_b128 v[244:247], v171 offset:22528
	ds_read_b128 v[248:251], v146 offset:22528
	s_nop 15
	s_nop 15
	s_waitcnt lgkmcnt(0)
	s_barrier
	s_setprio 1
	v_mfma_f32_16x16x32_bf16 v[140:143], v[32:35], v[186:189], v[140:143]
	v_mfma_f32_16x16x32_bf16 v[136:139], v[40:43], v[186:189], v[136:139]
	v_mfma_f32_16x16x32_bf16 v[124:127], v[32:35], v[194:197], v[124:127]
	v_mfma_f32_16x16x32_bf16 v[120:123], v[40:43], v[194:197], v[120:123]
	v_mfma_f32_16x16x32_bf16 v[108:111], v[32:35], v[202:205], v[108:111]
	v_mfma_f32_16x16x32_bf16 v[104:107], v[40:43], v[202:205], v[104:107]
	v_mfma_f32_16x16x32_bf16 v[92:95], v[32:35], v[210:213], v[92:95]
	v_mfma_f32_16x16x32_bf16 v[88:91], v[40:43], v[210:213], v[88:91]
	v_mfma_f32_16x16x32_bf16 v[140:143], v[36:39], v[190:193], v[140:143]
	v_mfma_f32_16x16x32_bf16 v[136:139], v[44:47], v[190:193], v[136:139]
	v_mfma_f32_16x16x32_bf16 v[124:127], v[36:39], v[198:201], v[124:127]
	v_mfma_f32_16x16x32_bf16 v[120:123], v[44:47], v[198:201], v[120:123]
	v_mfma_f32_16x16x32_bf16 v[108:111], v[36:39], v[206:209], v[108:111]
	v_mfma_f32_16x16x32_bf16 v[104:107], v[44:47], v[206:209], v[104:107]
	v_mfma_f32_16x16x32_bf16 v[92:95], v[36:39], v[214:217], v[92:95]
	v_mfma_f32_16x16x32_bf16 v[88:91], v[44:47], v[214:217], v[88:91]
	s_setprio 0
	s_setprio 1
	v_mfma_f32_16x16x32_bf16 v[132:135], v[162:165], v[186:189], v[132:135]
	v_mfma_f32_16x16x32_bf16 v[128:131], v[178:181], v[186:189], v[128:131]
	v_mfma_f32_16x16x32_bf16 v[116:119], v[162:165], v[194:197], v[116:119]
	v_mfma_f32_16x16x32_bf16 v[112:115], v[178:181], v[194:197], v[112:115]
	v_mfma_f32_16x16x32_bf16 v[100:103], v[162:165], v[202:205], v[100:103]
	v_mfma_f32_16x16x32_bf16 v[96:99], v[178:181], v[202:205], v[96:99]
	v_mfma_f32_16x16x32_bf16 v[84:87], v[162:165], v[210:213], v[84:87]
	v_mfma_f32_16x16x32_bf16 v[80:83], v[178:181], v[210:213], v[80:83]
	v_mfma_f32_16x16x32_bf16 v[132:135], v[174:177], v[190:193], v[132:135]
	v_mfma_f32_16x16x32_bf16 v[128:131], v[182:185], v[190:193], v[128:131]
	v_mfma_f32_16x16x32_bf16 v[116:119], v[174:177], v[198:201], v[116:119]
	v_mfma_f32_16x16x32_bf16 v[112:115], v[182:185], v[198:201], v[112:115]
	v_mfma_f32_16x16x32_bf16 v[100:103], v[174:177], v[206:209], v[100:103]
	v_mfma_f32_16x16x32_bf16 v[96:99], v[182:185], v[206:209], v[96:99]
	v_mfma_f32_16x16x32_bf16 v[84:87], v[174:177], v[214:217], v[84:87]
	v_mfma_f32_16x16x32_bf16 v[80:83], v[182:185], v[214:217], v[80:83]
	s_setprio 0
	s_setprio 1
	v_mfma_f32_16x16x32_bf16 v[76:79], v[32:35], v[220:223], v[76:79]
	v_mfma_f32_16x16x32_bf16 v[72:75], v[40:43], v[220:223], v[72:75]
	v_mfma_f32_16x16x32_bf16 v[60:63], v[32:35], v[228:231], v[60:63]
	v_mfma_f32_16x16x32_bf16 v[56:59], v[40:43], v[228:231], v[56:59]
	v_mfma_f32_16x16x32_bf16 v[28:31], v[32:35], v[236:239], v[28:31]
	v_mfma_f32_16x16x32_bf16 v[24:27], v[40:43], v[236:239], v[24:27]
	v_mfma_f32_16x16x32_bf16 v[12:15], v[32:35], v[244:247], v[12:15]
	v_mfma_f32_16x16x32_bf16 v[8:11], v[40:43], v[244:247], v[8:11]
	v_mfma_f32_16x16x32_bf16 v[76:79], v[36:39], v[224:227], v[76:79]
	v_mfma_f32_16x16x32_bf16 v[72:75], v[44:47], v[224:227], v[72:75]
	v_mfma_f32_16x16x32_bf16 v[60:63], v[36:39], v[232:235], v[60:63]
	v_mfma_f32_16x16x32_bf16 v[56:59], v[44:47], v[232:235], v[56:59]
	v_mfma_f32_16x16x32_bf16 v[28:31], v[36:39], v[240:243], v[28:31]
	v_mfma_f32_16x16x32_bf16 v[24:27], v[44:47], v[240:243], v[24:27]
	v_mfma_f32_16x16x32_bf16 v[12:15], v[36:39], v[248:251], v[12:15]
	v_mfma_f32_16x16x32_bf16 v[8:11], v[44:47], v[248:251], v[8:11]
	s_setprio 0
	s_setprio 1
	v_mfma_f32_16x16x32_bf16 v[68:71], v[162:165], v[220:223], v[68:71]
	v_mfma_f32_16x16x32_bf16 v[64:67], v[178:181], v[220:223], v[64:67]
	v_mfma_f32_16x16x32_bf16 v[52:55], v[162:165], v[228:231], v[52:55]
	v_mfma_f32_16x16x32_bf16 v[48:51], v[178:181], v[228:231], v[48:51]
	v_mfma_f32_16x16x32_bf16 v[20:23], v[162:165], v[236:239], v[20:23]
	v_mfma_f32_16x16x32_bf16 v[16:19], v[178:181], v[236:239], v[16:19]
	v_mfma_f32_16x16x32_bf16 v[4:7], v[162:165], v[244:247], v[4:7]
	v_mfma_f32_16x16x32_bf16 v[0:3], v[178:181], v[244:247], v[0:3]
	v_mfma_f32_16x16x32_bf16 v[68:71], v[174:177], v[224:227], v[68:71]
	v_mfma_f32_16x16x32_bf16 v[64:67], v[182:185], v[224:227], v[64:67]
	v_mfma_f32_16x16x32_bf16 v[52:55], v[174:177], v[232:235], v[52:55]
	v_mfma_f32_16x16x32_bf16 v[48:51], v[182:185], v[232:235], v[48:51]
	v_mfma_f32_16x16x32_bf16 v[20:23], v[174:177], v[240:243], v[20:23]
	v_mfma_f32_16x16x32_bf16 v[16:19], v[182:185], v[240:243], v[16:19]
	v_mfma_f32_16x16x32_bf16 v[4:7], v[174:177], v[248:251], v[4:7]
	v_mfma_f32_16x16x32_bf16 v[0:3], v[182:185], v[248:251], v[0:3]
	s_setprio 0
	s_waitcnt vmcnt(0)
	s_barrier
	s_add_u32 vcc_lo, s30, 0x0
	s_addc_u32 vcc_hi, s31, 0
	s_add_i32 m0, s37, 0x10000
	s_nop 0
	global_load_lds_dwordx4 v148, vcc
	s_add_u32 vcc_lo, vcc_lo, 0x20000
	s_addc_u32 vcc_hi, vcc_hi, 0
	s_add_i32 m0, s37, 0x11000
	s_nop 0
	global_load_lds_dwordx4 v148, vcc
	s_add_u32 vcc_lo, vcc_lo, 0x20000
	s_addc_u32 vcc_hi, vcc_hi, 0
	s_add_i32 m0, s37, 0x12000
	s_nop 0
	global_load_lds_dwordx4 v148, vcc
	s_add_u32 vcc_lo, vcc_lo, 0x20000
	s_addc_u32 vcc_hi, vcc_hi, 0
	s_add_i32 m0, s37, 0x13000
	s_nop 0
	global_load_lds_dwordx4 v148, vcc
	s_add_u32 vcc_lo, vcc_lo, 0x20000
	s_addc_u32 vcc_hi, vcc_hi, 0
	s_add_i32 m0, s37, 0x14000
	s_nop 0
	global_load_lds_dwordx4 v148, vcc
	s_add_u32 vcc_lo, vcc_lo, 0x20000
	s_addc_u32 vcc_hi, vcc_hi, 0
	s_add_i32 m0, s37, 0x15000
	s_nop 0
	global_load_lds_dwordx4 v148, vcc
	s_add_u32 vcc_lo, vcc_lo, 0x20000
	s_addc_u32 vcc_hi, vcc_hi, 0
	s_add_i32 m0, s37, 0x16000
	s_nop 0
	global_load_lds_dwordx4 v148, vcc
	s_add_u32 vcc_lo, vcc_lo, 0x20000
	s_addc_u32 vcc_hi, vcc_hi, 0
	s_add_i32 m0, s37, 0x17000
	s_nop 0
	global_load_lds_dwordx4 v148, vcc
	ds_read_b128 v[32:35], v169 offset:32768
	ds_read_b128 v[36:39], v170 offset:32768
	ds_read_b128 v[40:43], v169 offset:34816
	ds_read_b128 v[44:47], v170 offset:34816
	ds_read_b128 v[162:165], v169 offset:49152
	ds_read_b128 v[174:177], v170 offset:49152
	ds_read_b128 v[178:181], v169 offset:51200
	ds_read_b128 v[182:185], v170 offset:51200
	ds_read_b128 v[186:189], v171 offset:32768
	ds_read_b128 v[190:193], v146 offset:32768
	ds_read_b128 v[194:197], v171 offset:34816
	ds_read_b128 v[198:201], v146 offset:34816
	ds_read_b128 v[202:205], v171 offset:36864
	ds_read_b128 v[206:209], v146 offset:36864
	ds_read_b128 v[210:213], v171 offset:38912
	ds_read_b128 v[214:217], v146 offset:38912
	ds_read_b128 v[220:223], v171 offset:49152
	ds_read_b128 v[224:227], v146 offset:49152
	ds_read_b128 v[228:231], v171 offset:51200
	ds_read_b128 v[232:235], v146 offset:51200
	ds_read_b128 v[236:239], v171 offset:53248
	ds_read_b128 v[240:243], v146 offset:53248
	ds_read_b128 v[244:247], v171 offset:55296
	ds_read_b128 v[248:251], v146 offset:55296
	s_nop 15
	s_nop 15
	s_waitcnt lgkmcnt(0)
	s_barrier
	s_setprio 1
	v_mfma_f32_16x16x32_bf16 v[140:143], v[32:35], v[186:189], v[140:143]
	v_mfma_f32_16x16x32_bf16 v[136:139], v[40:43], v[186:189], v[136:139]
	v_mfma_f32_16x16x32_bf16 v[124:127], v[32:35], v[194:197], v[124:127]
	v_mfma_f32_16x16x32_bf16 v[120:123], v[40:43], v[194:197], v[120:123]
	v_mfma_f32_16x16x32_bf16 v[108:111], v[32:35], v[202:205], v[108:111]
	v_mfma_f32_16x16x32_bf16 v[104:107], v[40:43], v[202:205], v[104:107]
	v_mfma_f32_16x16x32_bf16 v[92:95], v[32:35], v[210:213], v[92:95]
	v_mfma_f32_16x16x32_bf16 v[88:91], v[40:43], v[210:213], v[88:91]
	v_mfma_f32_16x16x32_bf16 v[140:143], v[36:39], v[190:193], v[140:143]
	v_mfma_f32_16x16x32_bf16 v[136:139], v[44:47], v[190:193], v[136:139]
	v_mfma_f32_16x16x32_bf16 v[124:127], v[36:39], v[198:201], v[124:127]
	v_mfma_f32_16x16x32_bf16 v[120:123], v[44:47], v[198:201], v[120:123]
	v_mfma_f32_16x16x32_bf16 v[108:111], v[36:39], v[206:209], v[108:111]
	v_mfma_f32_16x16x32_bf16 v[104:107], v[44:47], v[206:209], v[104:107]
	v_mfma_f32_16x16x32_bf16 v[92:95], v[36:39], v[214:217], v[92:95]
	v_mfma_f32_16x16x32_bf16 v[88:91], v[44:47], v[214:217], v[88:91]
	s_setprio 0
	s_setprio 1
	v_mfma_f32_16x16x32_bf16 v[132:135], v[162:165], v[186:189], v[132:135]
	v_mfma_f32_16x16x32_bf16 v[128:131], v[178:181], v[186:189], v[128:131]
	v_mfma_f32_16x16x32_bf16 v[116:119], v[162:165], v[194:197], v[116:119]
	v_mfma_f32_16x16x32_bf16 v[112:115], v[178:181], v[194:197], v[112:115]
	v_mfma_f32_16x16x32_bf16 v[100:103], v[162:165], v[202:205], v[100:103]
	v_mfma_f32_16x16x32_bf16 v[96:99], v[178:181], v[202:205], v[96:99]
	v_mfma_f32_16x16x32_bf16 v[84:87], v[162:165], v[210:213], v[84:87]
	v_mfma_f32_16x16x32_bf16 v[80:83], v[178:181], v[210:213], v[80:83]
	v_mfma_f32_16x16x32_bf16 v[132:135], v[174:177], v[190:193], v[132:135]
	v_mfma_f32_16x16x32_bf16 v[128:131], v[182:185], v[190:193], v[128:131]
	v_mfma_f32_16x16x32_bf16 v[116:119], v[174:177], v[198:201], v[116:119]
	v_mfma_f32_16x16x32_bf16 v[112:115], v[182:185], v[198:201], v[112:115]
	v_mfma_f32_16x16x32_bf16 v[100:103], v[174:177], v[206:209], v[100:103]
	v_mfma_f32_16x16x32_bf16 v[96:99], v[182:185], v[206:209], v[96:99]
	v_mfma_f32_16x16x32_bf16 v[84:87], v[174:177], v[214:217], v[84:87]
	v_mfma_f32_16x16x32_bf16 v[80:83], v[182:185], v[214:217], v[80:83]
	s_setprio 0
	s_setprio 1
	v_mfma_f32_16x16x32_bf16 v[76:79], v[32:35], v[220:223], v[76:79]
	v_mfma_f32_16x16x32_bf16 v[72:75], v[40:43], v[220:223], v[72:75]
	v_mfma_f32_16x16x32_bf16 v[60:63], v[32:35], v[228:231], v[60:63]
	v_mfma_f32_16x16x32_bf16 v[56:59], v[40:43], v[228:231], v[56:59]
	v_mfma_f32_16x16x32_bf16 v[28:31], v[32:35], v[236:239], v[28:31]
	v_mfma_f32_16x16x32_bf16 v[24:27], v[40:43], v[236:239], v[24:27]
	v_mfma_f32_16x16x32_bf16 v[12:15], v[32:35], v[244:247], v[12:15]
	v_mfma_f32_16x16x32_bf16 v[8:11], v[40:43], v[244:247], v[8:11]
	v_mfma_f32_16x16x32_bf16 v[76:79], v[36:39], v[224:227], v[76:79]
	v_mfma_f32_16x16x32_bf16 v[72:75], v[44:47], v[224:227], v[72:75]
	v_mfma_f32_16x16x32_bf16 v[60:63], v[36:39], v[232:235], v[60:63]
	v_mfma_f32_16x16x32_bf16 v[56:59], v[44:47], v[232:235], v[56:59]
	v_mfma_f32_16x16x32_bf16 v[28:31], v[36:39], v[240:243], v[28:31]
	v_mfma_f32_16x16x32_bf16 v[24:27], v[44:47], v[240:243], v[24:27]
	v_mfma_f32_16x16x32_bf16 v[12:15], v[36:39], v[248:251], v[12:15]
	v_mfma_f32_16x16x32_bf16 v[8:11], v[44:47], v[248:251], v[8:11]
	s_setprio 0
	s_setprio 1
	v_mfma_f32_16x16x32_bf16 v[68:71], v[162:165], v[220:223], v[68:71]
	v_mfma_f32_16x16x32_bf16 v[64:67], v[178:181], v[220:223], v[64:67]
	v_mfma_f32_16x16x32_bf16 v[52:55], v[162:165], v[228:231], v[52:55]
	v_mfma_f32_16x16x32_bf16 v[48:51], v[178:181], v[228:231], v[48:51]
	v_mfma_f32_16x16x32_bf16 v[20:23], v[162:165], v[236:239], v[20:23]
	v_mfma_f32_16x16x32_bf16 v[16:19], v[178:181], v[236:239], v[16:19]
	v_mfma_f32_16x16x32_bf16 v[4:7], v[162:165], v[244:247], v[4:7]
	v_mfma_f32_16x16x32_bf16 v[0:3], v[178:181], v[244:247], v[0:3]
	v_mfma_f32_16x16x32_bf16 v[68:71], v[174:177], v[224:227], v[68:71]
	v_mfma_f32_16x16x32_bf16 v[64:67], v[182:185], v[224:227], v[64:67]
	v_mfma_f32_16x16x32_bf16 v[52:55], v[174:177], v[232:235], v[52:55]
	v_mfma_f32_16x16x32_bf16 v[48:51], v[182:185], v[232:235], v[48:51]
	v_mfma_f32_16x16x32_bf16 v[20:23], v[174:177], v[240:243], v[20:23]
	v_mfma_f32_16x16x32_bf16 v[16:19], v[182:185], v[240:243], v[16:19]
	v_mfma_f32_16x16x32_bf16 v[4:7], v[174:177], v[248:251], v[4:7]
	v_mfma_f32_16x16x32_bf16 v[0:3], v[182:185], v[248:251], v[0:3]
	s_setprio 0
	s_waitcnt vmcnt(0)
	s_barrier
	s_add_i32 s56, s56, 2
	s_add_u32 s12, s12, 0x100
	s_addc_u32 s13, s13, 0
	s_add_u32 s54, s54, 0x100
	s_addc_u32 s55, s55, 0
	s_cmp_gt_u32 s56, 29
	s_cbranch_scc0 .LBB0_846
	s_branch .Lk64_done_p6
.Lk64_trail_p6:
	s_sub_u32 vcc_lo, s12, 0x40000
	s_subb_u32 vcc_hi, s13, 0
	s_add_i32 m0, s37, 0x9000
	s_nop 0
	global_load_lds_dwordx4 v150, vcc
	s_add_u32 vcc_lo, vcc_lo, 0x20000
	s_addc_u32 vcc_hi, vcc_hi, 0
	s_add_i32 m0, s37, 0xa000
	s_nop 0
	global_load_lds_dwordx4 v150, vcc
	s_add_u32 vcc_lo, vcc_lo, 0x60000
	s_addc_u32 vcc_hi, vcc_hi, 0
	s_add_i32 m0, s37, 0xd000
	s_nop 0
	global_load_lds_dwordx4 v150, vcc
	s_add_u32 vcc_lo, vcc_lo, 0x20000
	s_addc_u32 vcc_hi, vcc_hi, 0
	s_add_i32 m0, s37, 0xe000
	s_nop 0
	global_load_lds_dwordx4 v150, vcc
	s_add_u32 vcc_lo, s34, 0x0
	s_addc_u32 vcc_hi, s35, 0
	s_sub_i32 m0, s37, 0x1000
	s_nop 0
	global_load_lds_dwordx4 v150, vcc
	s_add_u32 vcc_lo, vcc_lo, 0x20000
	s_addc_u32 vcc_hi, vcc_hi, 0
	s_mov_b32 m0, s37
	s_nop 0
	global_load_lds_dwordx4 v150, vcc
	s_add_u32 vcc_lo, vcc_lo, 0x60000
	s_addc_u32 vcc_hi, vcc_hi, 0
	s_add_i32 m0, s37, 0x3000
	s_nop 0
	global_load_lds_dwordx4 v150, vcc
	s_add_u32 vcc_lo, vcc_lo, 0x20000
	s_addc_u32 vcc_hi, vcc_hi, 0
	s_add_i32 m0, s37, 0x4000
	s_nop 0
	global_load_lds_dwordx4 v150, vcc
	ds_read_b128 v[32:35], v169 offset:0
	ds_read_b128 v[36:39], v170 offset:0
	ds_read_b128 v[40:43], v169 offset:2048
	ds_read_b128 v[44:47], v170 offset:2048
	ds_read_b128 v[162:165], v169 offset:16384
	ds_read_b128 v[174:177], v170 offset:16384
	ds_read_b128 v[178:181], v169 offset:18432
	ds_read_b128 v[182:185], v170 offset:18432
	ds_read_b128 v[186:189], v171 offset:0
	ds_read_b128 v[190:193], v146 offset:0
	ds_read_b128 v[194:197], v171 offset:2048
	ds_read_b128 v[198:201], v146 offset:2048
	ds_read_b128 v[202:205], v171 offset:4096
	ds_read_b128 v[206:209], v146 offset:4096
	ds_read_b128 v[210:213], v171 offset:6144
	ds_read_b128 v[214:217], v146 offset:6144
	ds_read_b128 v[220:223], v171 offset:16384
	ds_read_b128 v[224:227], v146 offset:16384
	ds_read_b128 v[228:231], v171 offset:18432
	ds_read_b128 v[232:235], v146 offset:18432
	ds_read_b128 v[236:239], v171 offset:20480
	ds_read_b128 v[240:243], v146 offset:20480
	ds_read_b128 v[244:247], v171 offset:22528
	ds_read_b128 v[248:251], v146 offset:22528
	s_nop 15
	s_nop 15
	s_waitcnt lgkmcnt(0)
	s_barrier
	s_setprio 1
	v_mfma_f32_16x16x32_bf16 v[140:143], v[32:35], v[186:189], v[140:143]
	v_mfma_f32_16x16x32_bf16 v[136:139], v[40:43], v[186:189], v[136:139]
	v_mfma_f32_16x16x32_bf16 v[124:127], v[32:35], v[194:197], v[124:127]
	v_mfma_f32_16x16x32_bf16 v[120:123], v[40:43], v[194:197], v[120:123]
	v_mfma_f32_16x16x32_bf16 v[108:111], v[32:35], v[202:205], v[108:111]
	v_mfma_f32_16x16x32_bf16 v[104:107], v[40:43], v[202:205], v[104:107]
	v_mfma_f32_16x16x32_bf16 v[92:95], v[32:35], v[210:213], v[92:95]
	v_mfma_f32_16x16x32_bf16 v[88:91], v[40:43], v[210:213], v[88:91]
	v_mfma_f32_16x16x32_bf16 v[140:143], v[36:39], v[190:193], v[140:143]
	v_mfma_f32_16x16x32_bf16 v[136:139], v[44:47], v[190:193], v[136:139]
	v_mfma_f32_16x16x32_bf16 v[124:127], v[36:39], v[198:201], v[124:127]
	v_mfma_f32_16x16x32_bf16 v[120:123], v[44:47], v[198:201], v[120:123]
	v_mfma_f32_16x16x32_bf16 v[108:111], v[36:39], v[206:209], v[108:111]
	v_mfma_f32_16x16x32_bf16 v[104:107], v[44:47], v[206:209], v[104:107]
	v_mfma_f32_16x16x32_bf16 v[92:95], v[36:39], v[214:217], v[92:95]
	v_mfma_f32_16x16x32_bf16 v[88:91], v[44:47], v[214:217], v[88:91]
	s_setprio 0
	s_setprio 1
	v_mfma_f32_16x16x32_bf16 v[132:135], v[162:165], v[186:189], v[132:135]
	v_mfma_f32_16x16x32_bf16 v[128:131], v[178:181], v[186:189], v[128:131]
	v_mfma_f32_16x16x32_bf16 v[116:119], v[162:165], v[194:197], v[116:119]
	v_mfma_f32_16x16x32_bf16 v[112:115], v[178:181], v[194:197], v[112:115]
	v_mfma_f32_16x16x32_bf16 v[100:103], v[162:165], v[202:205], v[100:103]
	v_mfma_f32_16x16x32_bf16 v[96:99], v[178:181], v[202:205], v[96:99]
	v_mfma_f32_16x16x32_bf16 v[84:87], v[162:165], v[210:213], v[84:87]
	v_mfma_f32_16x16x32_bf16 v[80:83], v[178:181], v[210:213], v[80:83]
	v_mfma_f32_16x16x32_bf16 v[132:135], v[174:177], v[190:193], v[132:135]
	v_mfma_f32_16x16x32_bf16 v[128:131], v[182:185], v[190:193], v[128:131]
	v_mfma_f32_16x16x32_bf16 v[116:119], v[174:177], v[198:201], v[116:119]
	v_mfma_f32_16x16x32_bf16 v[112:115], v[182:185], v[198:201], v[112:115]
	v_mfma_f32_16x16x32_bf16 v[100:103], v[174:177], v[206:209], v[100:103]
	v_mfma_f32_16x16x32_bf16 v[96:99], v[182:185], v[206:209], v[96:99]
	v_mfma_f32_16x16x32_bf16 v[84:87], v[174:177], v[214:217], v[84:87]
	v_mfma_f32_16x16x32_bf16 v[80:83], v[182:185], v[214:217], v[80:83]
	s_setprio 0
	s_setprio 1
	v_mfma_f32_16x16x32_bf16 v[76:79], v[32:35], v[220:223], v[76:79]
	v_mfma_f32_16x16x32_bf16 v[72:75], v[40:43], v[220:223], v[72:75]
	v_mfma_f32_16x16x32_bf16 v[60:63], v[32:35], v[228:231], v[60:63]
	v_mfma_f32_16x16x32_bf16 v[56:59], v[40:43], v[228:231], v[56:59]
	v_mfma_f32_16x16x32_bf16 v[28:31], v[32:35], v[236:239], v[28:31]
	v_mfma_f32_16x16x32_bf16 v[24:27], v[40:43], v[236:239], v[24:27]
	v_mfma_f32_16x16x32_bf16 v[12:15], v[32:35], v[244:247], v[12:15]
	v_mfma_f32_16x16x32_bf16 v[8:11], v[40:43], v[244:247], v[8:11]
	v_mfma_f32_16x16x32_bf16 v[76:79], v[36:39], v[224:227], v[76:79]
	v_mfma_f32_16x16x32_bf16 v[72:75], v[44:47], v[224:227], v[72:75]
	v_mfma_f32_16x16x32_bf16 v[60:63], v[36:39], v[232:235], v[60:63]
	v_mfma_f32_16x16x32_bf16 v[56:59], v[44:47], v[232:235], v[56:59]
	v_mfma_f32_16x16x32_bf16 v[28:31], v[36:39], v[240:243], v[28:31]
	v_mfma_f32_16x16x32_bf16 v[24:27], v[44:47], v[240:243], v[24:27]
	v_mfma_f32_16x16x32_bf16 v[12:15], v[36:39], v[248:251], v[12:15]
	v_mfma_f32_16x16x32_bf16 v[8:11], v[44:47], v[248:251], v[8:11]
	s_setprio 0
	s_setprio 1
	v_mfma_f32_16x16x32_bf16 v[68:71], v[162:165], v[220:223], v[68:71]
	v_mfma_f32_16x16x32_bf16 v[64:67], v[178:181], v[220:223], v[64:67]
	v_mfma_f32_16x16x32_bf16 v[52:55], v[162:165], v[228:231], v[52:55]
	v_mfma_f32_16x16x32_bf16 v[48:51], v[178:181], v[228:231], v[48:51]
	v_mfma_f32_16x16x32_bf16 v[20:23], v[162:165], v[236:239], v[20:23]
	v_mfma_f32_16x16x32_bf16 v[16:19], v[178:181], v[236:239], v[16:19]
	v_mfma_f32_16x16x32_bf16 v[4:7], v[162:165], v[244:247], v[4:7]
	v_mfma_f32_16x16x32_bf16 v[0:3], v[178:181], v[244:247], v[0:3]
	v_mfma_f32_16x16x32_bf16 v[68:71], v[174:177], v[224:227], v[68:71]
	v_mfma_f32_16x16x32_bf16 v[64:67], v[182:185], v[224:227], v[64:67]
	v_mfma_f32_16x16x32_bf16 v[52:55], v[174:177], v[232:235], v[52:55]
	v_mfma_f32_16x16x32_bf16 v[48:51], v[182:185], v[232:235], v[48:51]
	v_mfma_f32_16x16x32_bf16 v[20:23], v[174:177], v[240:243], v[20:23]
	v_mfma_f32_16x16x32_bf16 v[16:19], v[182:185], v[240:243], v[16:19]
	v_mfma_f32_16x16x32_bf16 v[4:7], v[174:177], v[248:251], v[4:7]
	v_mfma_f32_16x16x32_bf16 v[0:3], v[182:185], v[248:251], v[0:3]
	s_setprio 0
	s_waitcnt vmcnt(0)
	s_barrier
	s_add_u32 vcc_lo, s34, 0x40000
	s_addc_u32 vcc_hi, s35, 0
	s_add_i32 m0, s37, 0x1000
	s_nop 0
	global_load_lds_dwordx4 v150, vcc
	s_add_u32 vcc_lo, vcc_lo, 0x20000
	s_addc_u32 vcc_hi, vcc_hi, 0
	s_add_i32 m0, s37, 0x2000
	s_nop 0
	global_load_lds_dwordx4 v150, vcc
	s_add_u32 vcc_lo, vcc_lo, 0x60000
	s_addc_u32 vcc_hi, vcc_hi, 0
	s_add_i32 m0, s37, 0x5000
	s_nop 0
	global_load_lds_dwordx4 v150, vcc
	s_add_u32 vcc_lo, vcc_lo, 0x20000
	s_addc_u32 vcc_hi, vcc_hi, 0
	s_add_i32 m0, s37, 0x6000
	s_nop 0
	global_load_lds_dwordx4 v150, vcc
	s_add_u32 vcc_lo, s34, 0x80
	s_addc_u32 vcc_hi, s35, 0
	s_add_i32 m0, s37, 0x7000
	s_nop 0
	global_load_lds_dwordx4 v150, vcc
	s_add_u32 vcc_lo, vcc_lo, 0x20000
	s_addc_u32 vcc_hi, vcc_hi, 0
	s_add_i32 m0, s37, 0x8000
	s_nop 0
	global_load_lds_dwordx4 v150, vcc
	s_add_u32 vcc_lo, vcc_lo, 0x60000
	s_addc_u32 vcc_hi, vcc_hi, 0
	s_add_i32 m0, s37, 0xb000
	s_nop 0
	global_load_lds_dwordx4 v150, vcc
	s_add_u32 vcc_lo, vcc_lo, 0x20000
	s_addc_u32 vcc_hi, vcc_hi, 0
	s_add_i32 m0, s37, 0xc000
	s_nop 0
	global_load_lds_dwordx4 v150, vcc
	ds_read_b128 v[32:35], v169 offset:32768
	ds_read_b128 v[36:39], v170 offset:32768
	ds_read_b128 v[40:43], v169 offset:34816
	ds_read_b128 v[44:47], v170 offset:34816
	ds_read_b128 v[162:165], v169 offset:49152
	ds_read_b128 v[174:177], v170 offset:49152
	ds_read_b128 v[178:181], v169 offset:51200
	ds_read_b128 v[182:185], v170 offset:51200
	ds_read_b128 v[186:189], v171 offset:32768
	ds_read_b128 v[190:193], v146 offset:32768
	ds_read_b128 v[194:197], v171 offset:34816
	ds_read_b128 v[198:201], v146 offset:34816
	ds_read_b128 v[202:205], v171 offset:36864
	ds_read_b128 v[206:209], v146 offset:36864
	ds_read_b128 v[210:213], v171 offset:38912
	ds_read_b128 v[214:217], v146 offset:38912
	ds_read_b128 v[220:223], v171 offset:49152
	ds_read_b128 v[224:227], v146 offset:49152
	ds_read_b128 v[228:231], v171 offset:51200
	ds_read_b128 v[232:235], v146 offset:51200
	ds_read_b128 v[236:239], v171 offset:53248
	ds_read_b128 v[240:243], v146 offset:53248
	ds_read_b128 v[244:247], v171 offset:55296
	ds_read_b128 v[248:251], v146 offset:55296
	s_nop 15
	s_nop 15
	s_waitcnt lgkmcnt(0)
	s_barrier
	s_setprio 1
	v_mfma_f32_16x16x32_bf16 v[140:143], v[32:35], v[186:189], v[140:143]
	v_mfma_f32_16x16x32_bf16 v[136:139], v[40:43], v[186:189], v[136:139]
	v_mfma_f32_16x16x32_bf16 v[124:127], v[32:35], v[194:197], v[124:127]
	v_mfma_f32_16x16x32_bf16 v[120:123], v[40:43], v[194:197], v[120:123]
	v_mfma_f32_16x16x32_bf16 v[108:111], v[32:35], v[202:205], v[108:111]
	v_mfma_f32_16x16x32_bf16 v[104:107], v[40:43], v[202:205], v[104:107]
	v_mfma_f32_16x16x32_bf16 v[92:95], v[32:35], v[210:213], v[92:95]
	v_mfma_f32_16x16x32_bf16 v[88:91], v[40:43], v[210:213], v[88:91]
	v_mfma_f32_16x16x32_bf16 v[140:143], v[36:39], v[190:193], v[140:143]
	v_mfma_f32_16x16x32_bf16 v[136:139], v[44:47], v[190:193], v[136:139]
	v_mfma_f32_16x16x32_bf16 v[124:127], v[36:39], v[198:201], v[124:127]
	v_mfma_f32_16x16x32_bf16 v[120:123], v[44:47], v[198:201], v[120:123]
	v_mfma_f32_16x16x32_bf16 v[108:111], v[36:39], v[206:209], v[108:111]
	v_mfma_f32_16x16x32_bf16 v[104:107], v[44:47], v[206:209], v[104:107]
	v_mfma_f32_16x16x32_bf16 v[92:95], v[36:39], v[214:217], v[92:95]
	v_mfma_f32_16x16x32_bf16 v[88:91], v[44:47], v[214:217], v[88:91]
	s_setprio 0
	s_setprio 1
	v_mfma_f32_16x16x32_bf16 v[132:135], v[162:165], v[186:189], v[132:135]
	v_mfma_f32_16x16x32_bf16 v[128:131], v[178:181], v[186:189], v[128:131]
	v_mfma_f32_16x16x32_bf16 v[116:119], v[162:165], v[194:197], v[116:119]
	v_mfma_f32_16x16x32_bf16 v[112:115], v[178:181], v[194:197], v[112:115]
	v_mfma_f32_16x16x32_bf16 v[100:103], v[162:165], v[202:205], v[100:103]
	v_mfma_f32_16x16x32_bf16 v[96:99], v[178:181], v[202:205], v[96:99]
	v_mfma_f32_16x16x32_bf16 v[84:87], v[162:165], v[210:213], v[84:87]
	v_mfma_f32_16x16x32_bf16 v[80:83], v[178:181], v[210:213], v[80:83]
	v_mfma_f32_16x16x32_bf16 v[132:135], v[174:177], v[190:193], v[132:135]
	v_mfma_f32_16x16x32_bf16 v[128:131], v[182:185], v[190:193], v[128:131]
	v_mfma_f32_16x16x32_bf16 v[116:119], v[174:177], v[198:201], v[116:119]
	v_mfma_f32_16x16x32_bf16 v[112:115], v[182:185], v[198:201], v[112:115]
	v_mfma_f32_16x16x32_bf16 v[100:103], v[174:177], v[206:209], v[100:103]
	v_mfma_f32_16x16x32_bf16 v[96:99], v[182:185], v[206:209], v[96:99]
	v_mfma_f32_16x16x32_bf16 v[84:87], v[174:177], v[214:217], v[84:87]
	v_mfma_f32_16x16x32_bf16 v[80:83], v[182:185], v[214:217], v[80:83]
	s_setprio 0
	s_setprio 1
	v_mfma_f32_16x16x32_bf16 v[76:79], v[32:35], v[220:223], v[76:79]
	v_mfma_f32_16x16x32_bf16 v[72:75], v[40:43], v[220:223], v[72:75]
	v_mfma_f32_16x16x32_bf16 v[60:63], v[32:35], v[228:231], v[60:63]
	v_mfma_f32_16x16x32_bf16 v[56:59], v[40:43], v[228:231], v[56:59]
	v_mfma_f32_16x16x32_bf16 v[28:31], v[32:35], v[236:239], v[28:31]
	v_mfma_f32_16x16x32_bf16 v[24:27], v[40:43], v[236:239], v[24:27]
	v_mfma_f32_16x16x32_bf16 v[12:15], v[32:35], v[244:247], v[12:15]
	v_mfma_f32_16x16x32_bf16 v[8:11], v[40:43], v[244:247], v[8:11]
	v_mfma_f32_16x16x32_bf16 v[76:79], v[36:39], v[224:227], v[76:79]
	v_mfma_f32_16x16x32_bf16 v[72:75], v[44:47], v[224:227], v[72:75]
	v_mfma_f32_16x16x32_bf16 v[60:63], v[36:39], v[232:235], v[60:63]
	v_mfma_f32_16x16x32_bf16 v[56:59], v[44:47], v[232:235], v[56:59]
	v_mfma_f32_16x16x32_bf16 v[28:31], v[36:39], v[240:243], v[28:31]
	v_mfma_f32_16x16x32_bf16 v[24:27], v[44:47], v[240:243], v[24:27]
	v_mfma_f32_16x16x32_bf16 v[12:15], v[36:39], v[248:251], v[12:15]
	v_mfma_f32_16x16x32_bf16 v[8:11], v[44:47], v[248:251], v[8:11]
	s_setprio 0
	s_setprio 1
	v_mfma_f32_16x16x32_bf16 v[68:71], v[162:165], v[220:223], v[68:71]
	v_mfma_f32_16x16x32_bf16 v[64:67], v[178:181], v[220:223], v[64:67]
	v_mfma_f32_16x16x32_bf16 v[52:55], v[162:165], v[228:231], v[52:55]
	v_mfma_f32_16x16x32_bf16 v[48:51], v[178:181], v[228:231], v[48:51]
	v_mfma_f32_16x16x32_bf16 v[20:23], v[162:165], v[236:239], v[20:23]
	v_mfma_f32_16x16x32_bf16 v[16:19], v[178:181], v[236:239], v[16:19]
	v_mfma_f32_16x16x32_bf16 v[4:7], v[162:165], v[244:247], v[4:7]
	v_mfma_f32_16x16x32_bf16 v[0:3], v[178:181], v[244:247], v[0:3]
	v_mfma_f32_16x16x32_bf16 v[68:71], v[174:177], v[224:227], v[68:71]
	v_mfma_f32_16x16x32_bf16 v[64:67], v[182:185], v[224:227], v[64:67]
	v_mfma_f32_16x16x32_bf16 v[52:55], v[174:177], v[232:235], v[52:55]
	v_mfma_f32_16x16x32_bf16 v[48:51], v[182:185], v[232:235], v[48:51]
	v_mfma_f32_16x16x32_bf16 v[20:23], v[174:177], v[240:243], v[20:23]
	v_mfma_f32_16x16x32_bf16 v[16:19], v[182:185], v[240:243], v[16:19]
	v_mfma_f32_16x16x32_bf16 v[4:7], v[174:177], v[248:251], v[4:7]
	v_mfma_f32_16x16x32_bf16 v[0:3], v[182:185], v[248:251], v[0:3]
	s_setprio 0
	s_waitcnt vmcnt(0)
	s_barrier
	s_add_i32 s56, s56, 2
	s_add_u32 s12, s12, 0x100
	s_addc_u32 s13, s13, 0
	s_add_u32 s54, s54, 0x100
	s_addc_u32 s55, s55, 0
	s_cmp_gt_u32 s56, 29
	s_cbranch_scc0 .LBB0_846
